# gMLP units v2: coalescing-friendly lane mappings (two lanes per position when staging, 16-byte U loads/HEADS stores via permuted channel-to-tile assignment) cut VMEM issue time
# speedup vs baseline: 1.0150x; 1.0150x over previous
.Lseam0_cont:
	s_cbranch_vccz .LBB0_583
	s_mov_b64 s[6:7], s[46:47]
	v_mov_b32_e32 v83, v194
	v_readlane_b32 s4, v245, 58
	v_bfe_u32 v0, v83, 4, 2
	s_add_u32 s0, s6, 0x8200000
	v_lshlrev_b32_e32 v1, 2, v0
	v_lshl_add_u32 v82, v0, 4, 0
	v_lshlrev_b32_e32 v0, 3, v0
	v_readlane_b32 s5, v245, 59
	s_addc_u32 s1, s7, 0
	v_and_b32_e32 v84, 15, v83
	v_readfirstlane_b32 s12, v83
	s_andn2_b64 vcc, exec, s[4:5]
	v_lshlrev_b32_e32 v0, 1, v0
	v_lshlrev_b32_e32 v2, 1, v1
	s_cbranch_vccnz .LBB0_575
	v_lshrrev_b32_e32 v77, 1, v83
	v_and_b32_e32 v77, 0x7f, v77
	v_and_b32_e32 v155, 1, v83
	v_lshrrev_b32_e32 v89, 8, v83
	v_mul_u32_u24_e32 v1, 0x60, v77
	v_mul_u32_u24_e32 v154, 48, v155
	v_add_u32_e32 v1, v1, v154
	v_mul_u32_u24_e32 v85, 0x600, v77
	v_lshl_add_u32 v85, v89, 7, v85
	v_lshl_add_u32 v85, v155, 6, v85
	v_lshl_add_u32 v154, v89, 1, v155
	v_mul_u32_u24_e32 v86, 0x2200, v154
	v_lshl_add_u32 v86, v77, 1, v86
	v_lshlrev_b32_e32 v88, 7, v154
	v_add_u32_e32 v88, 0x9000, v88
	v_and_b32_e32 v154, 15, v197
	v_lshrrev_b32_e32 v155, 4, v197
	v_lshrrev_b32_e32 v87, 2, v154
	v_lshlrev_b32_e32 v87, 3, v87
	v_and_b32_e32 v77, 3, v154
	v_add_u32_e32 v87, v87, v77
	v_mul_u32_u24_e32 v87, 0x110, v87
	v_lshl_add_u32 v87, v155, 4, v87
	v_readfirstlane_b32 s19, v83
	s_nop 3
	s_lshr_b32 s19, s19, 6
	v_lshl_add_u32 v189, s19, 4, v154
	v_lshlrev_b32_e32 v90, 8, v189
	v_lshl_add_u32 v90, v155, 4, v90
	v_lshlrev_b32_e32 v91, 2, v189
	v_mul_u32_u24_e32 v92, 0x600, v189
	v_lshl_add_u32 v92, v155, 4, v92
	v_lshlrev_b32_e32 v93, 11, v189
	v_lshl_add_u32 v93, v155, 4, v93
	v_readlane_b32 s72, v246, 15
	v_readlane_b32 s73, v246, 16
	v_readlane_b32 s74, v246, 17
	v_readlane_b32 s75, v246, 18
	v_readlane_b32 s78, v246, 21
	v_readlane_b32 s79, v246, 22
	v_lshlrev_b32_e32 v77, 4, v83
	s_movk_i32 s28, 0xc0
	v_cmp_gt_u32_e32 vcc, s28, v83
	s_and_saveexec_b64 s[28:29], vcc
	s_cbranch_execz .Lgm_ng1
	global_load_dwordx4 v[200:203], v77, s[72:73]
	global_load_dwordx4 v[204:207], v77, s[74:75]
.Lgm_ng1:
	s_mov_b64 exec, s[28:29]
	s_mov_b32 s16, s2
	s_mul_hi_u32 s18, s16, 0xaaaaaaab
	s_lshr_b32 s18, s18, 2
	s_mul_i32 s17, s18, 6
	s_sub_u32 s17, s16, s17
	s_mul_i32 s28, s18, 0x3000
	s_add_u32 s4, s6, s28
	s_addc_u32 s5, s7, 0
	s_add_u32 s4, s4, 0x3600000
	s_addc_u32 s5, s5, 0
	global_load_dwordx4 v[4:7], v1, s[4:5]
	global_load_dwordx4 v[8:11], v1, s[4:5] offset:16
	global_load_dwordx4 v[12:15], v1, s[4:5] offset:32
	s_mul_i32 s28, s18, 0x30000
	s_lshl_b32 s29, s17, 8
	s_add_u32 s28, s28, s29
	s_add_u32 s8, s6, s28
	s_addc_u32 s9, s7, 0
	s_add_u32 s14, s8, 0xd200000
	s_addc_u32 s15, s9, 0
	s_add_u32 s8, s8, 0x10200000
	s_addc_u32 s9, s9, 0
	global_load_dwordx4 v[16:19], v85, s[8:9]
	global_load_dwordx4 v[20:23], v85, s[8:9] offset:16
	global_load_dwordx4 v[24:27], v85, s[8:9] offset:32
	global_load_dwordx4 v[28:31], v85, s[8:9] offset:48
	s_lshl_b32 s28, s17, 15
	s_add_u32 s10, s6, s28
	s_addc_u32 s11, s7, 0
	s_add_u32 s10, s10, 0x3200000
	s_addc_u32 s11, s11, 0
	global_load_dwordx4 v[32:35], v90, s[10:11]
	global_load_dwordx4 v[36:39], v90, s[10:11] offset:64
	global_load_dwordx4 v[40:43], v90, s[10:11] offset:128
	global_load_dwordx4 v[44:47], v90, s[10:11] offset:192
	s_lshl_b32 s28, s17, 9
	s_add_u32 s12, s78, s28
	s_addc_u32 s13, s79, 0
	global_load_dword v64, v91, s[12:13]
	global_load_dwordx4 v[48:51], v92, s[14:15]
	global_load_dwordx4 v[52:55], v92, s[14:15] offset:64
	global_load_dwordx4 v[56:59], v92, s[14:15] offset:128
	global_load_dwordx4 v[60:63], v92, s[14:15] offset:192
	s_waitcnt vmcnt(16)
	s_movk_i32 s28, 0xc0
	v_cmp_gt_u32_e32 vcc, s28, v83
	s_and_saveexec_b64 s[28:29], vcc
	s_cbranch_execz .Lgm_ng2
	v_lshlrev_b32_e32 v77, 4, v83
	v_add_u32_e32 v77, 0x9000, v77
	ds_write_b128 v77, v[200:203]
	ds_write_b128 v77, v[204:207] offset:3072
.Lgm_ng2:
	s_mov_b64 exec, s[28:29]
	s_waitcnt lgkmcnt(0)
	s_barrier
	s_add_u32 s70, s16, s92
	s_min_u32 s71, s70, 0x5ff
	s_mul_hi_u32 s18, s71, 0xaaaaaaab
	s_lshr_b32 s18, s18, 2
	s_mul_i32 s17, s18, 6
	s_sub_u32 s17, s71, s17
	s_mul_i32 s28, s18, 0x3000
	s_add_u32 s4, s6, s28
	s_addc_u32 s5, s7, 0
	s_add_u32 s4, s4, 0x3600000
	s_addc_u32 s5, s5, 0
	global_load_dwordx4 v[98:101], v1, s[4:5]
	global_load_dwordx4 v[102:105], v1, s[4:5] offset:16
	global_load_dwordx4 v[106:109], v1, s[4:5] offset:32
	s_mul_i32 s28, s18, 0x30000
	s_lshl_b32 s29, s17, 8
	s_add_u32 s28, s28, s29
	s_add_u32 s8, s6, s28
	s_addc_u32 s9, s7, 0
	s_add_u32 s14, s8, 0xd200000
	s_addc_u32 s15, s9, 0
	s_add_u32 s8, s8, 0x10200000
	s_addc_u32 s9, s9, 0
	global_load_dwordx4 v[110:113], v85, s[8:9]
	global_load_dwordx4 v[114:117], v85, s[8:9] offset:16
	global_load_dwordx4 v[118:121], v85, s[8:9] offset:32
	global_load_dwordx4 v[122:125], v85, s[8:9] offset:48
	s_lshl_b32 s28, s17, 15
	s_add_u32 s10, s6, s28
	s_addc_u32 s11, s7, 0
	s_add_u32 s10, s10, 0x3200000
	s_addc_u32 s11, s11, 0
	global_load_dwordx4 v[126:129], v90, s[10:11]
	global_load_dwordx4 v[130:133], v90, s[10:11] offset:64
	global_load_dwordx4 v[134:137], v90, s[10:11] offset:128
	global_load_dwordx4 v[138:141], v90, s[10:11] offset:192
	s_lshl_b32 s28, s17, 9
	s_add_u32 s12, s78, s28
	s_addc_u32 s13, s79, 0
	global_load_dword v188, v91, s[12:13]
	global_load_dwordx4 v[172:175], v92, s[14:15]
	global_load_dwordx4 v[176:179], v92, s[14:15] offset:64
	global_load_dwordx4 v[180:183], v92, s[14:15] offset:128
	global_load_dwordx4 v[184:187], v92, s[14:15] offset:192
	s_mul_hi_u32 s18, s16, 0xaaaaaaab
	s_lshr_b32 s18, s18, 2
	s_mul_i32 s17, s18, 6
	s_sub_u32 s17, s16, s17
	s_lshl_b32 s28, s17, 9
	v_add_u32_e32 v89, s28, v88
	s_mul_i32 s28, s18, 0x40000
	s_lshl_b32 s29, s17, 8
	s_add_u32 s28, s28, s29
	s_add_u32 s68, s0, s28
	s_addc_u32 s69, s1, 0
	s_waitcnt vmcnt(25)
	ds_read_b128 v[200:203], v89
	ds_read_b128 v[204:207], v89 offset:16
	ds_read_b128 v[208:211], v89 offset:3072
	ds_read_b128 v[212:215], v89 offset:3088
	v_add_f32_e32 v77, v4, v6
	v_add_f32_e32 v154, v5, v7
	v_add_f32_e32 v155, v8, v10
	v_add_f32_e32 v189, v9, v11
	v_add_f32_e32 v77, v77, v155
	v_add_f32_e32 v154, v154, v189
	v_add_f32_e32 v155, v12, v14
	v_add_f32_e32 v189, v13, v15
	v_add_f32_e32 v77, v77, v155
	v_add_f32_e32 v154, v154, v189
	s_nop 1
	v_add_f32_dpp v77, v77, v77 quad_perm:[1,0,3,2] row_mask:0xf bank_mask:0xf
	v_add_f32_dpp v154, v154, v154 quad_perm:[1,0,3,2] row_mask:0xf bank_mask:0xf
	v_mul_f32_e32 v155, 0x3aaaaaab, v77
	v_mul_f32_e32 v155, v155, v155
	s_mov_b32 s28, 0x3aaaaaab
	v_fma_f32 v154, v154, s28, -v155
	v_add_f32_e32 v154, 0x358637bd, v154
	v_rsq_f32_e32 v154, v154
	ds_read_b128 v[216:219], v89 offset:32
	ds_read_b128 v[220:223], v89 offset:48
	ds_read_b128 v[224:227], v89 offset:3104
	ds_read_b128 v[228:231], v89 offset:3120
	s_waitcnt lgkmcnt(4)
	v_lshlrev_b32_e32 v155, 16, v16
	v_and_b32_e32 v189, 0xffff0000, v16
	v_fmac_f32_e32 v155, 0xbaaaaaab, v77
	v_fmac_f32_e32 v189, 0xbaaaaaab, v77
	v_mul_f32_e32 v155, v155, v154
	v_mul_f32_e32 v189, v189, v154
	v_fma_f32 v155, v200, v155, v208
	v_fma_f32 v189, v201, v189, v209
	v_cvt_pk_bf16_f32 v16, v155, v189
	ds_write_b16 v86, v16
	ds_write_b16_d16_hi v86, v16 offset:272
	v_lshlrev_b32_e32 v155, 16, v17
	v_and_b32_e32 v189, 0xffff0000, v17
	v_fmac_f32_e32 v155, 0xbaaaaaab, v77
	v_fmac_f32_e32 v189, 0xbaaaaaab, v77
	v_mul_f32_e32 v155, v155, v154
	v_mul_f32_e32 v189, v189, v154
	v_fma_f32 v155, v202, v155, v210
	v_fma_f32 v189, v203, v189, v211
	v_cvt_pk_bf16_f32 v17, v155, v189
	ds_write_b16 v86, v17 offset:544
	ds_write_b16_d16_hi v86, v17 offset:816
	v_lshlrev_b32_e32 v155, 16, v18
	v_and_b32_e32 v189, 0xffff0000, v18
	v_fmac_f32_e32 v155, 0xbaaaaaab, v77
	v_fmac_f32_e32 v189, 0xbaaaaaab, v77
	v_mul_f32_e32 v155, v155, v154
	v_mul_f32_e32 v189, v189, v154
	v_fma_f32 v155, v204, v155, v212
	v_fma_f32 v189, v205, v189, v213
	v_cvt_pk_bf16_f32 v18, v155, v189
	ds_write_b16 v86, v18 offset:1088
	ds_write_b16_d16_hi v86, v18 offset:1360
	v_lshlrev_b32_e32 v155, 16, v19
	v_and_b32_e32 v189, 0xffff0000, v19
	v_fmac_f32_e32 v155, 0xbaaaaaab, v77
	v_fmac_f32_e32 v189, 0xbaaaaaab, v77
	v_mul_f32_e32 v155, v155, v154
	v_mul_f32_e32 v189, v189, v154
	v_fma_f32 v155, v206, v155, v214
	v_fma_f32 v189, v207, v189, v215
	v_cvt_pk_bf16_f32 v19, v155, v189
	ds_write_b16 v86, v19 offset:1632
	ds_write_b16_d16_hi v86, v19 offset:1904
	ds_read_b128 v[200:203], v89 offset:64
	ds_read_b128 v[204:207], v89 offset:80
	ds_read_b128 v[208:211], v89 offset:3136
	ds_read_b128 v[212:215], v89 offset:3152
	s_waitcnt lgkmcnt(4)
	v_lshlrev_b32_e32 v155, 16, v20
	v_and_b32_e32 v189, 0xffff0000, v20
	v_fmac_f32_e32 v155, 0xbaaaaaab, v77
	v_fmac_f32_e32 v189, 0xbaaaaaab, v77
	v_mul_f32_e32 v155, v155, v154
	v_mul_f32_e32 v189, v189, v154
	v_fma_f32 v155, v216, v155, v224
	v_fma_f32 v189, v217, v189, v225
	v_cvt_pk_bf16_f32 v20, v155, v189
	ds_write_b16 v86, v20 offset:2176
	ds_write_b16_d16_hi v86, v20 offset:2448
	v_lshlrev_b32_e32 v155, 16, v21
	v_and_b32_e32 v189, 0xffff0000, v21
	v_fmac_f32_e32 v155, 0xbaaaaaab, v77
	v_fmac_f32_e32 v189, 0xbaaaaaab, v77
	v_mul_f32_e32 v155, v155, v154
	v_mul_f32_e32 v189, v189, v154
	v_fma_f32 v155, v218, v155, v226
	v_fma_f32 v189, v219, v189, v227
	v_cvt_pk_bf16_f32 v21, v155, v189
	ds_write_b16 v86, v21 offset:2720
	ds_write_b16_d16_hi v86, v21 offset:2992
	v_lshlrev_b32_e32 v155, 16, v22
	v_and_b32_e32 v189, 0xffff0000, v22
	v_fmac_f32_e32 v155, 0xbaaaaaab, v77
	v_fmac_f32_e32 v189, 0xbaaaaaab, v77
	v_mul_f32_e32 v155, v155, v154
	v_mul_f32_e32 v189, v189, v154
	v_fma_f32 v155, v220, v155, v228
	v_fma_f32 v189, v221, v189, v229
	v_cvt_pk_bf16_f32 v22, v155, v189
	ds_write_b16 v86, v22 offset:3264
	ds_write_b16_d16_hi v86, v22 offset:3536
	v_lshlrev_b32_e32 v155, 16, v23
	v_and_b32_e32 v189, 0xffff0000, v23
	v_fmac_f32_e32 v155, 0xbaaaaaab, v77
	v_fmac_f32_e32 v189, 0xbaaaaaab, v77
	v_mul_f32_e32 v155, v155, v154
	v_mul_f32_e32 v189, v189, v154
	v_fma_f32 v155, v222, v155, v230
	v_fma_f32 v189, v223, v189, v231
	v_cvt_pk_bf16_f32 v23, v155, v189
	ds_write_b16 v86, v23 offset:3808
	ds_write_b16_d16_hi v86, v23 offset:4080
	ds_read_b128 v[216:219], v89 offset:96
	ds_read_b128 v[220:223], v89 offset:112
	ds_read_b128 v[224:227], v89 offset:3168
	ds_read_b128 v[228:231], v89 offset:3184
	s_waitcnt lgkmcnt(4)
	v_lshlrev_b32_e32 v155, 16, v24
	v_and_b32_e32 v189, 0xffff0000, v24
	v_fmac_f32_e32 v155, 0xbaaaaaab, v77
	v_fmac_f32_e32 v189, 0xbaaaaaab, v77
	v_mul_f32_e32 v155, v155, v154
	v_mul_f32_e32 v189, v189, v154
	v_fma_f32 v155, v200, v155, v208
	v_fma_f32 v189, v201, v189, v209
	v_cvt_pk_bf16_f32 v24, v155, v189
	ds_write_b16 v86, v24 offset:4352
	ds_write_b16_d16_hi v86, v24 offset:4624
	v_lshlrev_b32_e32 v155, 16, v25
	v_and_b32_e32 v189, 0xffff0000, v25
	v_fmac_f32_e32 v155, 0xbaaaaaab, v77
	v_fmac_f32_e32 v189, 0xbaaaaaab, v77
	v_mul_f32_e32 v155, v155, v154
	v_mul_f32_e32 v189, v189, v154
	v_fma_f32 v155, v202, v155, v210
	v_fma_f32 v189, v203, v189, v211
	v_cvt_pk_bf16_f32 v25, v155, v189
	ds_write_b16 v86, v25 offset:4896
	ds_write_b16_d16_hi v86, v25 offset:5168
	v_lshlrev_b32_e32 v155, 16, v26
	v_and_b32_e32 v189, 0xffff0000, v26
	v_fmac_f32_e32 v155, 0xbaaaaaab, v77
	v_fmac_f32_e32 v189, 0xbaaaaaab, v77
	v_mul_f32_e32 v155, v155, v154
	v_mul_f32_e32 v189, v189, v154
	v_fma_f32 v155, v204, v155, v212
	v_fma_f32 v189, v205, v189, v213
	v_cvt_pk_bf16_f32 v26, v155, v189
	ds_write_b16 v86, v26 offset:5440
	ds_write_b16_d16_hi v86, v26 offset:5712
	v_lshlrev_b32_e32 v155, 16, v27
	v_and_b32_e32 v189, 0xffff0000, v27
	v_fmac_f32_e32 v155, 0xbaaaaaab, v77
	v_fmac_f32_e32 v189, 0xbaaaaaab, v77
	v_mul_f32_e32 v155, v155, v154
	v_mul_f32_e32 v189, v189, v154
	v_fma_f32 v155, v206, v155, v214
	v_fma_f32 v189, v207, v189, v215
	v_cvt_pk_bf16_f32 v27, v155, v189
	ds_write_b16 v86, v27 offset:5984
	ds_write_b16_d16_hi v86, v27 offset:6256
	s_waitcnt lgkmcnt(0)
	v_lshlrev_b32_e32 v155, 16, v28
	v_and_b32_e32 v189, 0xffff0000, v28
	v_fmac_f32_e32 v155, 0xbaaaaaab, v77
	v_fmac_f32_e32 v189, 0xbaaaaaab, v77
	v_mul_f32_e32 v155, v155, v154
	v_mul_f32_e32 v189, v189, v154
	v_fma_f32 v155, v216, v155, v224
	v_fma_f32 v189, v217, v189, v225
	v_cvt_pk_bf16_f32 v28, v155, v189
	ds_write_b16 v86, v28 offset:6528
	ds_write_b16_d16_hi v86, v28 offset:6800
	v_lshlrev_b32_e32 v155, 16, v29
	v_and_b32_e32 v189, 0xffff0000, v29
	v_fmac_f32_e32 v155, 0xbaaaaaab, v77
	v_fmac_f32_e32 v189, 0xbaaaaaab, v77
	v_mul_f32_e32 v155, v155, v154
	v_mul_f32_e32 v189, v189, v154
	v_fma_f32 v155, v218, v155, v226
	v_fma_f32 v189, v219, v189, v227
	v_cvt_pk_bf16_f32 v29, v155, v189
	ds_write_b16 v86, v29 offset:7072
	ds_write_b16_d16_hi v86, v29 offset:7344
	v_lshlrev_b32_e32 v155, 16, v30
	v_and_b32_e32 v189, 0xffff0000, v30
	v_fmac_f32_e32 v155, 0xbaaaaaab, v77
	v_fmac_f32_e32 v189, 0xbaaaaaab, v77
	v_mul_f32_e32 v155, v155, v154
	v_mul_f32_e32 v189, v189, v154
	v_fma_f32 v155, v220, v155, v228
	v_fma_f32 v189, v221, v189, v229
	v_cvt_pk_bf16_f32 v30, v155, v189
	ds_write_b16 v86, v30 offset:7616
	ds_write_b16_d16_hi v86, v30 offset:7888
	v_lshlrev_b32_e32 v155, 16, v31
	v_and_b32_e32 v189, 0xffff0000, v31
	v_fmac_f32_e32 v155, 0xbaaaaaab, v77
	v_fmac_f32_e32 v189, 0xbaaaaaab, v77
	v_mul_f32_e32 v155, v155, v154
	v_mul_f32_e32 v189, v189, v154
	v_fma_f32 v155, v222, v155, v230
	v_fma_f32 v189, v223, v189, v231
	v_cvt_pk_bf16_f32 v31, v155, v189
	ds_write_b16 v86, v31 offset:8160
	ds_write_b16_d16_hi v86, v31 offset:8432
	s_waitcnt lgkmcnt(0)
	s_barrier
	s_waitcnt vmcnt(16)
	ds_read_b128 v[200:203], v87 offset:0
	ds_read_b128 v[204:207], v87 offset:64
	ds_read_b128 v[208:211], v87 offset:128
	ds_read_b128 v[212:215], v87 offset:192
	ds_read_b128 v[216:219], v87 offset:1088
	ds_read_b128 v[220:223], v87 offset:1152
	ds_read_b128 v[224:227], v87 offset:1216
	ds_read_b128 v[228:231], v87 offset:1280
	s_waitcnt lgkmcnt(4)
	v_mfma_f32_16x16x32_bf16 v[78:81], v[200:203], v[32:35], 0
	v_mfma_f32_16x16x32_bf16 v[78:81], v[204:207], v[36:39], v[78:81]
	v_mfma_f32_16x16x32_bf16 v[78:81], v[208:211], v[40:43], v[78:81]
	v_mfma_f32_16x16x32_bf16 v[78:81], v[212:215], v[44:47], v[78:81]
	ds_read_b128 v[200:203], v87 offset:8704
	ds_read_b128 v[204:207], v87 offset:8768
	ds_read_b128 v[208:211], v87 offset:8832
	ds_read_b128 v[212:215], v87 offset:8896
	s_waitcnt lgkmcnt(4)
	v_mfma_f32_16x16x32_bf16 v[94:97], v[216:219], v[32:35], 0
	v_mfma_f32_16x16x32_bf16 v[94:97], v[220:223], v[36:39], v[94:97]
	v_mfma_f32_16x16x32_bf16 v[94:97], v[224:227], v[40:43], v[94:97]
	v_mfma_f32_16x16x32_bf16 v[94:97], v[228:231], v[44:47], v[94:97]
	ds_read_b128 v[216:219], v87 offset:9792
	ds_read_b128 v[220:223], v87 offset:9856
	ds_read_b128 v[224:227], v87 offset:9920
	ds_read_b128 v[228:231], v87 offset:9984
	s_waitcnt lgkmcnt(4)
	v_mfma_f32_16x16x32_bf16 v[142:145], v[200:203], v[32:35], 0
	v_mfma_f32_16x16x32_bf16 v[142:145], v[204:207], v[36:39], v[142:145]
	v_mfma_f32_16x16x32_bf16 v[142:145], v[208:211], v[40:43], v[142:145]
	v_mfma_f32_16x16x32_bf16 v[142:145], v[212:215], v[44:47], v[142:145]
	ds_read_b128 v[200:203], v87 offset:17408
	ds_read_b128 v[204:207], v87 offset:17472
	ds_read_b128 v[208:211], v87 offset:17536
	ds_read_b128 v[212:215], v87 offset:17600
	v_add_f32_e32 v78, v64, v78
	v_add_f32_e32 v79, v64, v79
	v_add_f32_e32 v80, v64, v80
	v_add_f32_e32 v81, v64, v81
	v_lshlrev_b32_e32 v155, 16, v48
	v_and_b32_e32 v189, 0xffff0000, v48
	v_mul_f32_e32 v78, v78, v155
	v_mul_f32_e32 v79, v79, v189
	v_lshlrev_b32_e32 v155, 16, v49
	v_and_b32_e32 v189, 0xffff0000, v49
	v_mul_f32_e32 v80, v80, v155
	v_mul_f32_e32 v81, v81, v189
	v_cvt_pk_bf16_f32 v48, v78, v79
	v_cvt_pk_bf16_f32 v49, v80, v81
	v_add_f32_e32 v94, v64, v94
	v_add_f32_e32 v95, v64, v95
	v_add_f32_e32 v96, v64, v96
	v_add_f32_e32 v97, v64, v97
	v_lshlrev_b32_e32 v155, 16, v50
	v_and_b32_e32 v189, 0xffff0000, v50
	v_mul_f32_e32 v94, v94, v155
	v_mul_f32_e32 v95, v95, v189
	v_lshlrev_b32_e32 v155, 16, v51
	v_and_b32_e32 v189, 0xffff0000, v51
	v_mul_f32_e32 v96, v96, v155
	v_mul_f32_e32 v97, v97, v189
	v_cvt_pk_bf16_f32 v50, v94, v95
	v_cvt_pk_bf16_f32 v51, v96, v97
	global_store_dwordx4 v93, v[48:51], s[68:69]
	s_waitcnt lgkmcnt(4)
	v_mfma_f32_16x16x32_bf16 v[146:149], v[216:219], v[32:35], 0
	v_mfma_f32_16x16x32_bf16 v[146:149], v[220:223], v[36:39], v[146:149]
	v_mfma_f32_16x16x32_bf16 v[146:149], v[224:227], v[40:43], v[146:149]
	v_mfma_f32_16x16x32_bf16 v[146:149], v[228:231], v[44:47], v[146:149]
	ds_read_b128 v[216:219], v87 offset:18496
	ds_read_b128 v[220:223], v87 offset:18560
	ds_read_b128 v[224:227], v87 offset:18624
	ds_read_b128 v[228:231], v87 offset:18688
	s_waitcnt lgkmcnt(4)
	v_mfma_f32_16x16x32_bf16 v[78:81], v[200:203], v[32:35], 0
	v_mfma_f32_16x16x32_bf16 v[78:81], v[204:207], v[36:39], v[78:81]
	v_mfma_f32_16x16x32_bf16 v[78:81], v[208:211], v[40:43], v[78:81]
	v_mfma_f32_16x16x32_bf16 v[78:81], v[212:215], v[44:47], v[78:81]
	ds_read_b128 v[200:203], v87 offset:26112
	ds_read_b128 v[204:207], v87 offset:26176
	ds_read_b128 v[208:211], v87 offset:26240
	ds_read_b128 v[212:215], v87 offset:26304
	v_add_f32_e32 v142, v64, v142
	v_add_f32_e32 v143, v64, v143
	v_add_f32_e32 v144, v64, v144
	v_add_f32_e32 v145, v64, v145
	v_lshlrev_b32_e32 v155, 16, v52
	v_and_b32_e32 v189, 0xffff0000, v52
	v_mul_f32_e32 v142, v142, v155
	v_mul_f32_e32 v143, v143, v189
	v_lshlrev_b32_e32 v155, 16, v53
	v_and_b32_e32 v189, 0xffff0000, v53
	v_mul_f32_e32 v144, v144, v155
	v_mul_f32_e32 v145, v145, v189
	v_cvt_pk_bf16_f32 v52, v142, v143
	v_cvt_pk_bf16_f32 v53, v144, v145
	v_add_f32_e32 v146, v64, v146
	v_add_f32_e32 v147, v64, v147
	v_add_f32_e32 v148, v64, v148
	v_add_f32_e32 v149, v64, v149
	v_lshlrev_b32_e32 v155, 16, v54
	v_and_b32_e32 v189, 0xffff0000, v54
	v_mul_f32_e32 v146, v146, v155
	v_mul_f32_e32 v147, v147, v189
	v_lshlrev_b32_e32 v155, 16, v55
	v_and_b32_e32 v189, 0xffff0000, v55
	v_mul_f32_e32 v148, v148, v155
	v_mul_f32_e32 v149, v149, v189
	v_cvt_pk_bf16_f32 v54, v146, v147
	v_cvt_pk_bf16_f32 v55, v148, v149
	global_store_dwordx4 v93, v[52:55], s[68:69] offset:64
	s_waitcnt lgkmcnt(4)
	v_mfma_f32_16x16x32_bf16 v[94:97], v[216:219], v[32:35], 0
	v_mfma_f32_16x16x32_bf16 v[94:97], v[220:223], v[36:39], v[94:97]
	v_mfma_f32_16x16x32_bf16 v[94:97], v[224:227], v[40:43], v[94:97]
	v_mfma_f32_16x16x32_bf16 v[94:97], v[228:231], v[44:47], v[94:97]
	ds_read_b128 v[216:219], v87 offset:27200
	ds_read_b128 v[220:223], v87 offset:27264
	ds_read_b128 v[224:227], v87 offset:27328
	ds_read_b128 v[228:231], v87 offset:27392
	s_waitcnt lgkmcnt(4)
	v_mfma_f32_16x16x32_bf16 v[142:145], v[200:203], v[32:35], 0
	v_mfma_f32_16x16x32_bf16 v[142:145], v[204:207], v[36:39], v[142:145]
	v_mfma_f32_16x16x32_bf16 v[142:145], v[208:211], v[40:43], v[142:145]
	v_mfma_f32_16x16x32_bf16 v[142:145], v[212:215], v[44:47], v[142:145]
	v_add_f32_e32 v78, v64, v78
	v_add_f32_e32 v79, v64, v79
	v_add_f32_e32 v80, v64, v80
	v_add_f32_e32 v81, v64, v81
	v_lshlrev_b32_e32 v155, 16, v56
	v_and_b32_e32 v189, 0xffff0000, v56
	v_mul_f32_e32 v78, v78, v155
	v_mul_f32_e32 v79, v79, v189
	v_lshlrev_b32_e32 v155, 16, v57
	v_and_b32_e32 v189, 0xffff0000, v57
	v_mul_f32_e32 v80, v80, v155
	v_mul_f32_e32 v81, v81, v189
	v_cvt_pk_bf16_f32 v56, v78, v79
	v_cvt_pk_bf16_f32 v57, v80, v81
	v_add_f32_e32 v94, v64, v94
	v_add_f32_e32 v95, v64, v95
	v_add_f32_e32 v96, v64, v96
	v_add_f32_e32 v97, v64, v97
	v_lshlrev_b32_e32 v155, 16, v58
	v_and_b32_e32 v189, 0xffff0000, v58
	v_mul_f32_e32 v94, v94, v155
	v_mul_f32_e32 v95, v95, v189
	v_lshlrev_b32_e32 v155, 16, v59
	v_and_b32_e32 v189, 0xffff0000, v59
	v_mul_f32_e32 v96, v96, v155
	v_mul_f32_e32 v97, v97, v189
	v_cvt_pk_bf16_f32 v58, v94, v95
	v_cvt_pk_bf16_f32 v59, v96, v97
	global_store_dwordx4 v93, v[56:59], s[68:69] offset:128
	s_waitcnt lgkmcnt(0)
	v_mfma_f32_16x16x32_bf16 v[146:149], v[216:219], v[32:35], 0
	v_mfma_f32_16x16x32_bf16 v[146:149], v[220:223], v[36:39], v[146:149]
	v_mfma_f32_16x16x32_bf16 v[146:149], v[224:227], v[40:43], v[146:149]
	v_mfma_f32_16x16x32_bf16 v[146:149], v[228:231], v[44:47], v[146:149]
	s_nop 7
	v_add_f32_e32 v142, v64, v142
	v_add_f32_e32 v143, v64, v143
	v_add_f32_e32 v144, v64, v144
	v_add_f32_e32 v145, v64, v145
	v_lshlrev_b32_e32 v155, 16, v60
	v_and_b32_e32 v189, 0xffff0000, v60
	v_mul_f32_e32 v142, v142, v155
	v_mul_f32_e32 v143, v143, v189
	v_lshlrev_b32_e32 v155, 16, v61
	v_and_b32_e32 v189, 0xffff0000, v61
	v_mul_f32_e32 v144, v144, v155
	v_mul_f32_e32 v145, v145, v189
	v_cvt_pk_bf16_f32 v60, v142, v143
	v_cvt_pk_bf16_f32 v61, v144, v145
	v_add_f32_e32 v146, v64, v146
	v_add_f32_e32 v147, v64, v147
	v_add_f32_e32 v148, v64, v148
	v_add_f32_e32 v149, v64, v149
	v_lshlrev_b32_e32 v155, 16, v62
	v_and_b32_e32 v189, 0xffff0000, v62
	v_mul_f32_e32 v146, v146, v155
	v_mul_f32_e32 v147, v147, v189
	v_lshlrev_b32_e32 v155, 16, v63
	v_and_b32_e32 v189, 0xffff0000, v63
	v_mul_f32_e32 v148, v148, v155
	v_mul_f32_e32 v149, v149, v189
	v_cvt_pk_bf16_f32 v62, v146, v147
	v_cvt_pk_bf16_f32 v63, v148, v149
	global_store_dwordx4 v93, v[60:63], s[68:69] offset:192
	s_barrier
	s_mov_b32 s16, s70
	s_cmpk_lt_u32 s16, 0x600
	s_cbranch_scc0 .Lgm_done
.Lgm_loop:
	s_add_u32 s70, s16, s92
	s_min_u32 s71, s70, 0x5ff
	s_mul_hi_u32 s18, s71, 0xaaaaaaab
	s_lshr_b32 s18, s18, 2
	s_mul_i32 s17, s18, 6
	s_sub_u32 s17, s71, s17
	s_mul_i32 s28, s18, 0x3000
	s_add_u32 s4, s6, s28
	s_addc_u32 s5, s7, 0
	s_add_u32 s4, s4, 0x3600000
	s_addc_u32 s5, s5, 0
	global_load_dwordx4 v[4:7], v1, s[4:5]
	global_load_dwordx4 v[8:11], v1, s[4:5] offset:16
	global_load_dwordx4 v[12:15], v1, s[4:5] offset:32
	s_mul_i32 s28, s18, 0x30000
	s_lshl_b32 s29, s17, 8
	s_add_u32 s28, s28, s29
	s_add_u32 s8, s6, s28
	s_addc_u32 s9, s7, 0
	s_add_u32 s14, s8, 0xd200000
	s_addc_u32 s15, s9, 0
	s_add_u32 s8, s8, 0x10200000
	s_addc_u32 s9, s9, 0
	global_load_dwordx4 v[16:19], v85, s[8:9]
	global_load_dwordx4 v[20:23], v85, s[8:9] offset:16
	global_load_dwordx4 v[24:27], v85, s[8:9] offset:32
	global_load_dwordx4 v[28:31], v85, s[8:9] offset:48
	s_lshl_b32 s28, s17, 15
	s_add_u32 s10, s6, s28
	s_addc_u32 s11, s7, 0
	s_add_u32 s10, s10, 0x3200000
	s_addc_u32 s11, s11, 0
	global_load_dwordx4 v[32:35], v90, s[10:11]
	global_load_dwordx4 v[36:39], v90, s[10:11] offset:64
	global_load_dwordx4 v[40:43], v90, s[10:11] offset:128
	global_load_dwordx4 v[44:47], v90, s[10:11] offset:192
	s_lshl_b32 s28, s17, 9
	s_add_u32 s12, s78, s28
	s_addc_u32 s13, s79, 0
	global_load_dword v64, v91, s[12:13]
	global_load_dwordx4 v[48:51], v92, s[14:15]
	global_load_dwordx4 v[52:55], v92, s[14:15] offset:64
	global_load_dwordx4 v[56:59], v92, s[14:15] offset:128
	global_load_dwordx4 v[60:63], v92, s[14:15] offset:192
	s_mul_hi_u32 s18, s16, 0xaaaaaaab
	s_lshr_b32 s18, s18, 2
	s_mul_i32 s17, s18, 6
	s_sub_u32 s17, s16, s17
	s_lshl_b32 s28, s17, 9
	v_add_u32_e32 v89, s28, v88
	s_mul_i32 s28, s18, 0x40000
	s_lshl_b32 s29, s17, 8
	s_add_u32 s28, s28, s29
	s_add_u32 s68, s0, s28
	s_addc_u32 s69, s1, 0
	s_waitcnt vmcnt(29)
	ds_read_b128 v[200:203], v89
	ds_read_b128 v[204:207], v89 offset:16
	ds_read_b128 v[208:211], v89 offset:3072
	ds_read_b128 v[212:215], v89 offset:3088
	v_add_f32_e32 v77, v98, v100
	v_add_f32_e32 v154, v99, v101
	v_add_f32_e32 v155, v102, v104
	v_add_f32_e32 v189, v103, v105
	v_add_f32_e32 v77, v77, v155
	v_add_f32_e32 v154, v154, v189
	v_add_f32_e32 v155, v106, v108
	v_add_f32_e32 v189, v107, v109
	v_add_f32_e32 v77, v77, v155
	v_add_f32_e32 v154, v154, v189
	s_nop 1
	v_add_f32_dpp v77, v77, v77 quad_perm:[1,0,3,2] row_mask:0xf bank_mask:0xf
	v_add_f32_dpp v154, v154, v154 quad_perm:[1,0,3,2] row_mask:0xf bank_mask:0xf
	v_mul_f32_e32 v155, 0x3aaaaaab, v77
	v_mul_f32_e32 v155, v155, v155
	s_mov_b32 s28, 0x3aaaaaab
	v_fma_f32 v154, v154, s28, -v155
	v_add_f32_e32 v154, 0x358637bd, v154
	v_rsq_f32_e32 v154, v154
	ds_read_b128 v[216:219], v89 offset:32
	ds_read_b128 v[220:223], v89 offset:48
	ds_read_b128 v[224:227], v89 offset:3104
	ds_read_b128 v[228:231], v89 offset:3120
	s_waitcnt lgkmcnt(4)
	v_lshlrev_b32_e32 v155, 16, v110
	v_and_b32_e32 v189, 0xffff0000, v110
	v_fmac_f32_e32 v155, 0xbaaaaaab, v77
	v_fmac_f32_e32 v189, 0xbaaaaaab, v77
	v_mul_f32_e32 v155, v155, v154
	v_mul_f32_e32 v189, v189, v154
	v_fma_f32 v155, v200, v155, v208
	v_fma_f32 v189, v201, v189, v209
	v_cvt_pk_bf16_f32 v110, v155, v189
	ds_write_b16 v86, v110
	ds_write_b16_d16_hi v86, v110 offset:272
	v_lshlrev_b32_e32 v155, 16, v111
	v_and_b32_e32 v189, 0xffff0000, v111
	v_fmac_f32_e32 v155, 0xbaaaaaab, v77
	v_fmac_f32_e32 v189, 0xbaaaaaab, v77
	v_mul_f32_e32 v155, v155, v154
	v_mul_f32_e32 v189, v189, v154
	v_fma_f32 v155, v202, v155, v210
	v_fma_f32 v189, v203, v189, v211
	v_cvt_pk_bf16_f32 v111, v155, v189
	ds_write_b16 v86, v111 offset:544
	ds_write_b16_d16_hi v86, v111 offset:816
	v_lshlrev_b32_e32 v155, 16, v112
	v_and_b32_e32 v189, 0xffff0000, v112
	v_fmac_f32_e32 v155, 0xbaaaaaab, v77
	v_fmac_f32_e32 v189, 0xbaaaaaab, v77
	v_mul_f32_e32 v155, v155, v154
	v_mul_f32_e32 v189, v189, v154
	v_fma_f32 v155, v204, v155, v212
	v_fma_f32 v189, v205, v189, v213
	v_cvt_pk_bf16_f32 v112, v155, v189
	ds_write_b16 v86, v112 offset:1088
	ds_write_b16_d16_hi v86, v112 offset:1360
	v_lshlrev_b32_e32 v155, 16, v113
	v_and_b32_e32 v189, 0xffff0000, v113
	v_fmac_f32_e32 v155, 0xbaaaaaab, v77
	v_fmac_f32_e32 v189, 0xbaaaaaab, v77
	v_mul_f32_e32 v155, v155, v154
	v_mul_f32_e32 v189, v189, v154
	v_fma_f32 v155, v206, v155, v214
	v_fma_f32 v189, v207, v189, v215
	v_cvt_pk_bf16_f32 v113, v155, v189
	ds_write_b16 v86, v113 offset:1632
	ds_write_b16_d16_hi v86, v113 offset:1904
	ds_read_b128 v[200:203], v89 offset:64
	ds_read_b128 v[204:207], v89 offset:80
	ds_read_b128 v[208:211], v89 offset:3136
	ds_read_b128 v[212:215], v89 offset:3152
	s_waitcnt lgkmcnt(4)
	v_lshlrev_b32_e32 v155, 16, v114
	v_and_b32_e32 v189, 0xffff0000, v114
	v_fmac_f32_e32 v155, 0xbaaaaaab, v77
	v_fmac_f32_e32 v189, 0xbaaaaaab, v77
	v_mul_f32_e32 v155, v155, v154
	v_mul_f32_e32 v189, v189, v154
	v_fma_f32 v155, v216, v155, v224
	v_fma_f32 v189, v217, v189, v225
	v_cvt_pk_bf16_f32 v114, v155, v189
	ds_write_b16 v86, v114 offset:2176
	ds_write_b16_d16_hi v86, v114 offset:2448
	v_lshlrev_b32_e32 v155, 16, v115
	v_and_b32_e32 v189, 0xffff0000, v115
	v_fmac_f32_e32 v155, 0xbaaaaaab, v77
	v_fmac_f32_e32 v189, 0xbaaaaaab, v77
	v_mul_f32_e32 v155, v155, v154
	v_mul_f32_e32 v189, v189, v154
	v_fma_f32 v155, v218, v155, v226
	v_fma_f32 v189, v219, v189, v227
	v_cvt_pk_bf16_f32 v115, v155, v189
	ds_write_b16 v86, v115 offset:2720
	ds_write_b16_d16_hi v86, v115 offset:2992
	v_lshlrev_b32_e32 v155, 16, v116
	v_and_b32_e32 v189, 0xffff0000, v116
	v_fmac_f32_e32 v155, 0xbaaaaaab, v77
	v_fmac_f32_e32 v189, 0xbaaaaaab, v77
	v_mul_f32_e32 v155, v155, v154
	v_mul_f32_e32 v189, v189, v154
	v_fma_f32 v155, v220, v155, v228
	v_fma_f32 v189, v221, v189, v229
	v_cvt_pk_bf16_f32 v116, v155, v189
	ds_write_b16 v86, v116 offset:3264
	ds_write_b16_d16_hi v86, v116 offset:3536
	v_lshlrev_b32_e32 v155, 16, v117
	v_and_b32_e32 v189, 0xffff0000, v117
	v_fmac_f32_e32 v155, 0xbaaaaaab, v77
	v_fmac_f32_e32 v189, 0xbaaaaaab, v77
	v_mul_f32_e32 v155, v155, v154
	v_mul_f32_e32 v189, v189, v154
	v_fma_f32 v155, v222, v155, v230
	v_fma_f32 v189, v223, v189, v231
	v_cvt_pk_bf16_f32 v117, v155, v189
	ds_write_b16 v86, v117 offset:3808
	ds_write_b16_d16_hi v86, v117 offset:4080
	ds_read_b128 v[216:219], v89 offset:96
	ds_read_b128 v[220:223], v89 offset:112
	ds_read_b128 v[224:227], v89 offset:3168
	ds_read_b128 v[228:231], v89 offset:3184
	s_waitcnt lgkmcnt(4)
	v_lshlrev_b32_e32 v155, 16, v118
	v_and_b32_e32 v189, 0xffff0000, v118
	v_fmac_f32_e32 v155, 0xbaaaaaab, v77
	v_fmac_f32_e32 v189, 0xbaaaaaab, v77
	v_mul_f32_e32 v155, v155, v154
	v_mul_f32_e32 v189, v189, v154
	v_fma_f32 v155, v200, v155, v208
	v_fma_f32 v189, v201, v189, v209
	v_cvt_pk_bf16_f32 v118, v155, v189
	ds_write_b16 v86, v118 offset:4352
	ds_write_b16_d16_hi v86, v118 offset:4624
	v_lshlrev_b32_e32 v155, 16, v119
	v_and_b32_e32 v189, 0xffff0000, v119
	v_fmac_f32_e32 v155, 0xbaaaaaab, v77
	v_fmac_f32_e32 v189, 0xbaaaaaab, v77
	v_mul_f32_e32 v155, v155, v154
	v_mul_f32_e32 v189, v189, v154
	v_fma_f32 v155, v202, v155, v210
	v_fma_f32 v189, v203, v189, v211
	v_cvt_pk_bf16_f32 v119, v155, v189
	ds_write_b16 v86, v119 offset:4896
	ds_write_b16_d16_hi v86, v119 offset:5168
	v_lshlrev_b32_e32 v155, 16, v120
	v_and_b32_e32 v189, 0xffff0000, v120
	v_fmac_f32_e32 v155, 0xbaaaaaab, v77
	v_fmac_f32_e32 v189, 0xbaaaaaab, v77
	v_mul_f32_e32 v155, v155, v154
	v_mul_f32_e32 v189, v189, v154
	v_fma_f32 v155, v204, v155, v212
	v_fma_f32 v189, v205, v189, v213
	v_cvt_pk_bf16_f32 v120, v155, v189
	ds_write_b16 v86, v120 offset:5440
	ds_write_b16_d16_hi v86, v120 offset:5712
	v_lshlrev_b32_e32 v155, 16, v121
	v_and_b32_e32 v189, 0xffff0000, v121
	v_fmac_f32_e32 v155, 0xbaaaaaab, v77
	v_fmac_f32_e32 v189, 0xbaaaaaab, v77
	v_mul_f32_e32 v155, v155, v154
	v_mul_f32_e32 v189, v189, v154
	v_fma_f32 v155, v206, v155, v214
	v_fma_f32 v189, v207, v189, v215
	v_cvt_pk_bf16_f32 v121, v155, v189
	ds_write_b16 v86, v121 offset:5984
	ds_write_b16_d16_hi v86, v121 offset:6256
	s_waitcnt lgkmcnt(0)
	v_lshlrev_b32_e32 v155, 16, v122
	v_and_b32_e32 v189, 0xffff0000, v122
	v_fmac_f32_e32 v155, 0xbaaaaaab, v77
	v_fmac_f32_e32 v189, 0xbaaaaaab, v77
	v_mul_f32_e32 v155, v155, v154
	v_mul_f32_e32 v189, v189, v154
	v_fma_f32 v155, v216, v155, v224
	v_fma_f32 v189, v217, v189, v225
	v_cvt_pk_bf16_f32 v122, v155, v189
	ds_write_b16 v86, v122 offset:6528
	ds_write_b16_d16_hi v86, v122 offset:6800
	v_lshlrev_b32_e32 v155, 16, v123
	v_and_b32_e32 v189, 0xffff0000, v123
	v_fmac_f32_e32 v155, 0xbaaaaaab, v77
	v_fmac_f32_e32 v189, 0xbaaaaaab, v77
	v_mul_f32_e32 v155, v155, v154
	v_mul_f32_e32 v189, v189, v154
	v_fma_f32 v155, v218, v155, v226
	v_fma_f32 v189, v219, v189, v227
	v_cvt_pk_bf16_f32 v123, v155, v189
	ds_write_b16 v86, v123 offset:7072
	ds_write_b16_d16_hi v86, v123 offset:7344
	v_lshlrev_b32_e32 v155, 16, v124
	v_and_b32_e32 v189, 0xffff0000, v124
	v_fmac_f32_e32 v155, 0xbaaaaaab, v77
	v_fmac_f32_e32 v189, 0xbaaaaaab, v77
	v_mul_f32_e32 v155, v155, v154
	v_mul_f32_e32 v189, v189, v154
	v_fma_f32 v155, v220, v155, v228
	v_fma_f32 v189, v221, v189, v229
	v_cvt_pk_bf16_f32 v124, v155, v189
	ds_write_b16 v86, v124 offset:7616
	ds_write_b16_d16_hi v86, v124 offset:7888
	v_lshlrev_b32_e32 v155, 16, v125
	v_and_b32_e32 v189, 0xffff0000, v125
	v_fmac_f32_e32 v155, 0xbaaaaaab, v77
	v_fmac_f32_e32 v189, 0xbaaaaaab, v77
	v_mul_f32_e32 v155, v155, v154
	v_mul_f32_e32 v189, v189, v154
	v_fma_f32 v155, v222, v155, v230
	v_fma_f32 v189, v223, v189, v231
	v_cvt_pk_bf16_f32 v125, v155, v189
	ds_write_b16 v86, v125 offset:8160
	ds_write_b16_d16_hi v86, v125 offset:8432
	s_waitcnt lgkmcnt(0)
	s_barrier
	s_waitcnt vmcnt(20)
	ds_read_b128 v[200:203], v87 offset:0
	ds_read_b128 v[204:207], v87 offset:64
	ds_read_b128 v[208:211], v87 offset:128
	ds_read_b128 v[212:215], v87 offset:192
	ds_read_b128 v[216:219], v87 offset:1088
	ds_read_b128 v[220:223], v87 offset:1152
	ds_read_b128 v[224:227], v87 offset:1216
	ds_read_b128 v[228:231], v87 offset:1280
	s_waitcnt lgkmcnt(4)
	v_mfma_f32_16x16x32_bf16 v[78:81], v[200:203], v[126:129], 0
	v_mfma_f32_16x16x32_bf16 v[78:81], v[204:207], v[130:133], v[78:81]
	v_mfma_f32_16x16x32_bf16 v[78:81], v[208:211], v[134:137], v[78:81]
	v_mfma_f32_16x16x32_bf16 v[78:81], v[212:215], v[138:141], v[78:81]
	ds_read_b128 v[200:203], v87 offset:8704
	ds_read_b128 v[204:207], v87 offset:8768
	ds_read_b128 v[208:211], v87 offset:8832
	ds_read_b128 v[212:215], v87 offset:8896
	s_waitcnt lgkmcnt(4)
	v_mfma_f32_16x16x32_bf16 v[94:97], v[216:219], v[126:129], 0
	v_mfma_f32_16x16x32_bf16 v[94:97], v[220:223], v[130:133], v[94:97]
	v_mfma_f32_16x16x32_bf16 v[94:97], v[224:227], v[134:137], v[94:97]
	v_mfma_f32_16x16x32_bf16 v[94:97], v[228:231], v[138:141], v[94:97]
	ds_read_b128 v[216:219], v87 offset:9792
	ds_read_b128 v[220:223], v87 offset:9856
	ds_read_b128 v[224:227], v87 offset:9920
	ds_read_b128 v[228:231], v87 offset:9984
	s_waitcnt lgkmcnt(4)
	v_mfma_f32_16x16x32_bf16 v[142:145], v[200:203], v[126:129], 0
	v_mfma_f32_16x16x32_bf16 v[142:145], v[204:207], v[130:133], v[142:145]
	v_mfma_f32_16x16x32_bf16 v[142:145], v[208:211], v[134:137], v[142:145]
	v_mfma_f32_16x16x32_bf16 v[142:145], v[212:215], v[138:141], v[142:145]
	ds_read_b128 v[200:203], v87 offset:17408
	ds_read_b128 v[204:207], v87 offset:17472
	ds_read_b128 v[208:211], v87 offset:17536
	ds_read_b128 v[212:215], v87 offset:17600
	v_add_f32_e32 v78, v188, v78
	v_add_f32_e32 v79, v188, v79
	v_add_f32_e32 v80, v188, v80
	v_add_f32_e32 v81, v188, v81
	v_lshlrev_b32_e32 v155, 16, v172
	v_and_b32_e32 v189, 0xffff0000, v172
	v_mul_f32_e32 v78, v78, v155
	v_mul_f32_e32 v79, v79, v189
	v_lshlrev_b32_e32 v155, 16, v173
	v_and_b32_e32 v189, 0xffff0000, v173
	v_mul_f32_e32 v80, v80, v155
	v_mul_f32_e32 v81, v81, v189
	v_cvt_pk_bf16_f32 v172, v78, v79
	v_cvt_pk_bf16_f32 v173, v80, v81
	v_add_f32_e32 v94, v188, v94
	v_add_f32_e32 v95, v188, v95
	v_add_f32_e32 v96, v188, v96
	v_add_f32_e32 v97, v188, v97
	v_lshlrev_b32_e32 v155, 16, v174
	v_and_b32_e32 v189, 0xffff0000, v174
	v_mul_f32_e32 v94, v94, v155
	v_mul_f32_e32 v95, v95, v189
	v_lshlrev_b32_e32 v155, 16, v175
	v_and_b32_e32 v189, 0xffff0000, v175
	v_mul_f32_e32 v96, v96, v155
	v_mul_f32_e32 v97, v97, v189
	v_cvt_pk_bf16_f32 v174, v94, v95
	v_cvt_pk_bf16_f32 v175, v96, v97
	global_store_dwordx4 v93, v[172:175], s[68:69]
	s_waitcnt lgkmcnt(4)
	v_mfma_f32_16x16x32_bf16 v[146:149], v[216:219], v[126:129], 0
	v_mfma_f32_16x16x32_bf16 v[146:149], v[220:223], v[130:133], v[146:149]
	v_mfma_f32_16x16x32_bf16 v[146:149], v[224:227], v[134:137], v[146:149]
	v_mfma_f32_16x16x32_bf16 v[146:149], v[228:231], v[138:141], v[146:149]
	ds_read_b128 v[216:219], v87 offset:18496
	ds_read_b128 v[220:223], v87 offset:18560
	ds_read_b128 v[224:227], v87 offset:18624
	ds_read_b128 v[228:231], v87 offset:18688
	s_waitcnt lgkmcnt(4)
	v_mfma_f32_16x16x32_bf16 v[78:81], v[200:203], v[126:129], 0
	v_mfma_f32_16x16x32_bf16 v[78:81], v[204:207], v[130:133], v[78:81]
	v_mfma_f32_16x16x32_bf16 v[78:81], v[208:211], v[134:137], v[78:81]
	v_mfma_f32_16x16x32_bf16 v[78:81], v[212:215], v[138:141], v[78:81]
	ds_read_b128 v[200:203], v87 offset:26112
	ds_read_b128 v[204:207], v87 offset:26176
	ds_read_b128 v[208:211], v87 offset:26240
	ds_read_b128 v[212:215], v87 offset:26304
	v_add_f32_e32 v142, v188, v142
	v_add_f32_e32 v143, v188, v143
	v_add_f32_e32 v144, v188, v144
	v_add_f32_e32 v145, v188, v145
	v_lshlrev_b32_e32 v155, 16, v176
	v_and_b32_e32 v189, 0xffff0000, v176
	v_mul_f32_e32 v142, v142, v155
	v_mul_f32_e32 v143, v143, v189
	v_lshlrev_b32_e32 v155, 16, v177
	v_and_b32_e32 v189, 0xffff0000, v177
	v_mul_f32_e32 v144, v144, v155
	v_mul_f32_e32 v145, v145, v189
	v_cvt_pk_bf16_f32 v176, v142, v143
	v_cvt_pk_bf16_f32 v177, v144, v145
	v_add_f32_e32 v146, v188, v146
	v_add_f32_e32 v147, v188, v147
	v_add_f32_e32 v148, v188, v148
	v_add_f32_e32 v149, v188, v149
	v_lshlrev_b32_e32 v155, 16, v178
	v_and_b32_e32 v189, 0xffff0000, v178
	v_mul_f32_e32 v146, v146, v155
	v_mul_f32_e32 v147, v147, v189
	v_lshlrev_b32_e32 v155, 16, v179
	v_and_b32_e32 v189, 0xffff0000, v179
	v_mul_f32_e32 v148, v148, v155
	v_mul_f32_e32 v149, v149, v189
	v_cvt_pk_bf16_f32 v178, v146, v147
	v_cvt_pk_bf16_f32 v179, v148, v149
	global_store_dwordx4 v93, v[176:179], s[68:69] offset:64
	s_waitcnt lgkmcnt(4)
	v_mfma_f32_16x16x32_bf16 v[94:97], v[216:219], v[126:129], 0
	v_mfma_f32_16x16x32_bf16 v[94:97], v[220:223], v[130:133], v[94:97]
	v_mfma_f32_16x16x32_bf16 v[94:97], v[224:227], v[134:137], v[94:97]
	v_mfma_f32_16x16x32_bf16 v[94:97], v[228:231], v[138:141], v[94:97]
	ds_read_b128 v[216:219], v87 offset:27200
	ds_read_b128 v[220:223], v87 offset:27264
	ds_read_b128 v[224:227], v87 offset:27328
	ds_read_b128 v[228:231], v87 offset:27392
	s_waitcnt lgkmcnt(4)
	v_mfma_f32_16x16x32_bf16 v[142:145], v[200:203], v[126:129], 0
	v_mfma_f32_16x16x32_bf16 v[142:145], v[204:207], v[130:133], v[142:145]
	v_mfma_f32_16x16x32_bf16 v[142:145], v[208:211], v[134:137], v[142:145]
	v_mfma_f32_16x16x32_bf16 v[142:145], v[212:215], v[138:141], v[142:145]
	v_add_f32_e32 v78, v188, v78
	v_add_f32_e32 v79, v188, v79
	v_add_f32_e32 v80, v188, v80
	v_add_f32_e32 v81, v188, v81
	v_lshlrev_b32_e32 v155, 16, v180
	v_and_b32_e32 v189, 0xffff0000, v180
	v_mul_f32_e32 v78, v78, v155
	v_mul_f32_e32 v79, v79, v189
	v_lshlrev_b32_e32 v155, 16, v181
	v_and_b32_e32 v189, 0xffff0000, v181
	v_mul_f32_e32 v80, v80, v155
	v_mul_f32_e32 v81, v81, v189
	v_cvt_pk_bf16_f32 v180, v78, v79
	v_cvt_pk_bf16_f32 v181, v80, v81
	v_add_f32_e32 v94, v188, v94
	v_add_f32_e32 v95, v188, v95
	v_add_f32_e32 v96, v188, v96
	v_add_f32_e32 v97, v188, v97
	v_lshlrev_b32_e32 v155, 16, v182
	v_and_b32_e32 v189, 0xffff0000, v182
	v_mul_f32_e32 v94, v94, v155
	v_mul_f32_e32 v95, v95, v189
	v_lshlrev_b32_e32 v155, 16, v183
	v_and_b32_e32 v189, 0xffff0000, v183
	v_mul_f32_e32 v96, v96, v155
	v_mul_f32_e32 v97, v97, v189
	v_cvt_pk_bf16_f32 v182, v94, v95
	v_cvt_pk_bf16_f32 v183, v96, v97
	global_store_dwordx4 v93, v[180:183], s[68:69] offset:128
	s_waitcnt lgkmcnt(0)
	v_mfma_f32_16x16x32_bf16 v[146:149], v[216:219], v[126:129], 0
	v_mfma_f32_16x16x32_bf16 v[146:149], v[220:223], v[130:133], v[146:149]
	v_mfma_f32_16x16x32_bf16 v[146:149], v[224:227], v[134:137], v[146:149]
	v_mfma_f32_16x16x32_bf16 v[146:149], v[228:231], v[138:141], v[146:149]
	s_nop 7
	v_add_f32_e32 v142, v188, v142
	v_add_f32_e32 v143, v188, v143
	v_add_f32_e32 v144, v188, v144
	v_add_f32_e32 v145, v188, v145
	v_lshlrev_b32_e32 v155, 16, v184
	v_and_b32_e32 v189, 0xffff0000, v184
	v_mul_f32_e32 v142, v142, v155
	v_mul_f32_e32 v143, v143, v189
	v_lshlrev_b32_e32 v155, 16, v185
	v_and_b32_e32 v189, 0xffff0000, v185
	v_mul_f32_e32 v144, v144, v155
	v_mul_f32_e32 v145, v145, v189
	v_cvt_pk_bf16_f32 v184, v142, v143
	v_cvt_pk_bf16_f32 v185, v144, v145
	v_add_f32_e32 v146, v188, v146
	v_add_f32_e32 v147, v188, v147
	v_add_f32_e32 v148, v188, v148
	v_add_f32_e32 v149, v188, v149
	v_lshlrev_b32_e32 v155, 16, v186
	v_and_b32_e32 v189, 0xffff0000, v186
	v_mul_f32_e32 v146, v146, v155
	v_mul_f32_e32 v147, v147, v189
	v_lshlrev_b32_e32 v155, 16, v187
	v_and_b32_e32 v189, 0xffff0000, v187
	v_mul_f32_e32 v148, v148, v155
	v_mul_f32_e32 v149, v149, v189
	v_cvt_pk_bf16_f32 v186, v146, v147
	v_cvt_pk_bf16_f32 v187, v148, v149
	global_store_dwordx4 v93, v[184:187], s[68:69] offset:192
	s_barrier
	s_mov_b32 s16, s70
	s_cmpk_lt_u32 s16, 0x600
	s_cbranch_scc0 .Lgm_done
	s_add_u32 s70, s16, s92
	s_min_u32 s71, s70, 0x5ff
	s_mul_hi_u32 s18, s71, 0xaaaaaaab
	s_lshr_b32 s18, s18, 2
	s_mul_i32 s17, s18, 6
	s_sub_u32 s17, s71, s17
	s_mul_i32 s28, s18, 0x3000
	s_add_u32 s4, s6, s28
	s_addc_u32 s5, s7, 0
	s_add_u32 s4, s4, 0x3600000
	s_addc_u32 s5, s5, 0
	global_load_dwordx4 v[98:101], v1, s[4:5]
	global_load_dwordx4 v[102:105], v1, s[4:5] offset:16
	global_load_dwordx4 v[106:109], v1, s[4:5] offset:32
	s_mul_i32 s28, s18, 0x30000
	s_lshl_b32 s29, s17, 8
	s_add_u32 s28, s28, s29
	s_add_u32 s8, s6, s28
	s_addc_u32 s9, s7, 0
	s_add_u32 s14, s8, 0xd200000
	s_addc_u32 s15, s9, 0
	s_add_u32 s8, s8, 0x10200000
	s_addc_u32 s9, s9, 0
	global_load_dwordx4 v[110:113], v85, s[8:9]
	global_load_dwordx4 v[114:117], v85, s[8:9] offset:16
	global_load_dwordx4 v[118:121], v85, s[8:9] offset:32
	global_load_dwordx4 v[122:125], v85, s[8:9] offset:48
	s_lshl_b32 s28, s17, 15
	s_add_u32 s10, s6, s28
	s_addc_u32 s11, s7, 0
	s_add_u32 s10, s10, 0x3200000
	s_addc_u32 s11, s11, 0
	global_load_dwordx4 v[126:129], v90, s[10:11]
	global_load_dwordx4 v[130:133], v90, s[10:11] offset:64
	global_load_dwordx4 v[134:137], v90, s[10:11] offset:128
	global_load_dwordx4 v[138:141], v90, s[10:11] offset:192
	s_lshl_b32 s28, s17, 9
	s_add_u32 s12, s78, s28
	s_addc_u32 s13, s79, 0
	global_load_dword v188, v91, s[12:13]
	global_load_dwordx4 v[172:175], v92, s[14:15]
	global_load_dwordx4 v[176:179], v92, s[14:15] offset:64
	global_load_dwordx4 v[180:183], v92, s[14:15] offset:128
	global_load_dwordx4 v[184:187], v92, s[14:15] offset:192
	s_mul_hi_u32 s18, s16, 0xaaaaaaab
	s_lshr_b32 s18, s18, 2
	s_mul_i32 s17, s18, 6
	s_sub_u32 s17, s16, s17
	s_lshl_b32 s28, s17, 9
	v_add_u32_e32 v89, s28, v88
	s_mul_i32 s28, s18, 0x40000
	s_lshl_b32 s29, s17, 8
	s_add_u32 s28, s28, s29
	s_add_u32 s68, s0, s28
	s_addc_u32 s69, s1, 0
	s_waitcnt vmcnt(29)
	ds_read_b128 v[200:203], v89
	ds_read_b128 v[204:207], v89 offset:16
	ds_read_b128 v[208:211], v89 offset:3072
	ds_read_b128 v[212:215], v89 offset:3088
	v_add_f32_e32 v77, v4, v6
	v_add_f32_e32 v154, v5, v7
	v_add_f32_e32 v155, v8, v10
	v_add_f32_e32 v189, v9, v11
	v_add_f32_e32 v77, v77, v155
	v_add_f32_e32 v154, v154, v189
	v_add_f32_e32 v155, v12, v14
	v_add_f32_e32 v189, v13, v15
	v_add_f32_e32 v77, v77, v155
	v_add_f32_e32 v154, v154, v189
	s_nop 1
	v_add_f32_dpp v77, v77, v77 quad_perm:[1,0,3,2] row_mask:0xf bank_mask:0xf
	v_add_f32_dpp v154, v154, v154 quad_perm:[1,0,3,2] row_mask:0xf bank_mask:0xf
	v_mul_f32_e32 v155, 0x3aaaaaab, v77
	v_mul_f32_e32 v155, v155, v155
	s_mov_b32 s28, 0x3aaaaaab
	v_fma_f32 v154, v154, s28, -v155
	v_add_f32_e32 v154, 0x358637bd, v154
	v_rsq_f32_e32 v154, v154
	ds_read_b128 v[216:219], v89 offset:32
	ds_read_b128 v[220:223], v89 offset:48
	ds_read_b128 v[224:227], v89 offset:3104
	ds_read_b128 v[228:231], v89 offset:3120
	s_waitcnt lgkmcnt(4)
	v_lshlrev_b32_e32 v155, 16, v16
	v_and_b32_e32 v189, 0xffff0000, v16
	v_fmac_f32_e32 v155, 0xbaaaaaab, v77
	v_fmac_f32_e32 v189, 0xbaaaaaab, v77
	v_mul_f32_e32 v155, v155, v154
	v_mul_f32_e32 v189, v189, v154
	v_fma_f32 v155, v200, v155, v208
	v_fma_f32 v189, v201, v189, v209
	v_cvt_pk_bf16_f32 v16, v155, v189
	ds_write_b16 v86, v16
	ds_write_b16_d16_hi v86, v16 offset:272
	v_lshlrev_b32_e32 v155, 16, v17
	v_and_b32_e32 v189, 0xffff0000, v17
	v_fmac_f32_e32 v155, 0xbaaaaaab, v77
	v_fmac_f32_e32 v189, 0xbaaaaaab, v77
	v_mul_f32_e32 v155, v155, v154
	v_mul_f32_e32 v189, v189, v154
	v_fma_f32 v155, v202, v155, v210
	v_fma_f32 v189, v203, v189, v211
	v_cvt_pk_bf16_f32 v17, v155, v189
	ds_write_b16 v86, v17 offset:544
	ds_write_b16_d16_hi v86, v17 offset:816
	v_lshlrev_b32_e32 v155, 16, v18
	v_and_b32_e32 v189, 0xffff0000, v18
	v_fmac_f32_e32 v155, 0xbaaaaaab, v77
	v_fmac_f32_e32 v189, 0xbaaaaaab, v77
	v_mul_f32_e32 v155, v155, v154
	v_mul_f32_e32 v189, v189, v154
	v_fma_f32 v155, v204, v155, v212
	v_fma_f32 v189, v205, v189, v213
	v_cvt_pk_bf16_f32 v18, v155, v189
	ds_write_b16 v86, v18 offset:1088
	ds_write_b16_d16_hi v86, v18 offset:1360
	v_lshlrev_b32_e32 v155, 16, v19
	v_and_b32_e32 v189, 0xffff0000, v19
	v_fmac_f32_e32 v155, 0xbaaaaaab, v77
	v_fmac_f32_e32 v189, 0xbaaaaaab, v77
	v_mul_f32_e32 v155, v155, v154
	v_mul_f32_e32 v189, v189, v154
	v_fma_f32 v155, v206, v155, v214
	v_fma_f32 v189, v207, v189, v215
	v_cvt_pk_bf16_f32 v19, v155, v189
	ds_write_b16 v86, v19 offset:1632
	ds_write_b16_d16_hi v86, v19 offset:1904
	ds_read_b128 v[200:203], v89 offset:64
	ds_read_b128 v[204:207], v89 offset:80
	ds_read_b128 v[208:211], v89 offset:3136
	ds_read_b128 v[212:215], v89 offset:3152
	s_waitcnt lgkmcnt(4)
	v_lshlrev_b32_e32 v155, 16, v20
	v_and_b32_e32 v189, 0xffff0000, v20
	v_fmac_f32_e32 v155, 0xbaaaaaab, v77
	v_fmac_f32_e32 v189, 0xbaaaaaab, v77
	v_mul_f32_e32 v155, v155, v154
	v_mul_f32_e32 v189, v189, v154
	v_fma_f32 v155, v216, v155, v224
	v_fma_f32 v189, v217, v189, v225
	v_cvt_pk_bf16_f32 v20, v155, v189
	ds_write_b16 v86, v20 offset:2176
	ds_write_b16_d16_hi v86, v20 offset:2448
	v_lshlrev_b32_e32 v155, 16, v21
	v_and_b32_e32 v189, 0xffff0000, v21
	v_fmac_f32_e32 v155, 0xbaaaaaab, v77
	v_fmac_f32_e32 v189, 0xbaaaaaab, v77
	v_mul_f32_e32 v155, v155, v154
	v_mul_f32_e32 v189, v189, v154
	v_fma_f32 v155, v218, v155, v226
	v_fma_f32 v189, v219, v189, v227
	v_cvt_pk_bf16_f32 v21, v155, v189
	ds_write_b16 v86, v21 offset:2720
	ds_write_b16_d16_hi v86, v21 offset:2992
	v_lshlrev_b32_e32 v155, 16, v22
	v_and_b32_e32 v189, 0xffff0000, v22
	v_fmac_f32_e32 v155, 0xbaaaaaab, v77
	v_fmac_f32_e32 v189, 0xbaaaaaab, v77
	v_mul_f32_e32 v155, v155, v154
	v_mul_f32_e32 v189, v189, v154
	v_fma_f32 v155, v220, v155, v228
	v_fma_f32 v189, v221, v189, v229
	v_cvt_pk_bf16_f32 v22, v155, v189
	ds_write_b16 v86, v22 offset:3264
	ds_write_b16_d16_hi v86, v22 offset:3536
	v_lshlrev_b32_e32 v155, 16, v23
	v_and_b32_e32 v189, 0xffff0000, v23
	v_fmac_f32_e32 v155, 0xbaaaaaab, v77
	v_fmac_f32_e32 v189, 0xbaaaaaab, v77
	v_mul_f32_e32 v155, v155, v154
	v_mul_f32_e32 v189, v189, v154
	v_fma_f32 v155, v222, v155, v230
	v_fma_f32 v189, v223, v189, v231
	v_cvt_pk_bf16_f32 v23, v155, v189
	ds_write_b16 v86, v23 offset:3808
	ds_write_b16_d16_hi v86, v23 offset:4080
	ds_read_b128 v[216:219], v89 offset:96
	ds_read_b128 v[220:223], v89 offset:112
	ds_read_b128 v[224:227], v89 offset:3168
	ds_read_b128 v[228:231], v89 offset:3184
	s_waitcnt lgkmcnt(4)
	v_lshlrev_b32_e32 v155, 16, v24
	v_and_b32_e32 v189, 0xffff0000, v24
	v_fmac_f32_e32 v155, 0xbaaaaaab, v77
	v_fmac_f32_e32 v189, 0xbaaaaaab, v77
	v_mul_f32_e32 v155, v155, v154
	v_mul_f32_e32 v189, v189, v154
	v_fma_f32 v155, v200, v155, v208
	v_fma_f32 v189, v201, v189, v209
	v_cvt_pk_bf16_f32 v24, v155, v189
	ds_write_b16 v86, v24 offset:4352
	ds_write_b16_d16_hi v86, v24 offset:4624
	v_lshlrev_b32_e32 v155, 16, v25
	v_and_b32_e32 v189, 0xffff0000, v25
	v_fmac_f32_e32 v155, 0xbaaaaaab, v77
	v_fmac_f32_e32 v189, 0xbaaaaaab, v77
	v_mul_f32_e32 v155, v155, v154
	v_mul_f32_e32 v189, v189, v154
	v_fma_f32 v155, v202, v155, v210
	v_fma_f32 v189, v203, v189, v211
	v_cvt_pk_bf16_f32 v25, v155, v189
	ds_write_b16 v86, v25 offset:4896
	ds_write_b16_d16_hi v86, v25 offset:5168
	v_lshlrev_b32_e32 v155, 16, v26
	v_and_b32_e32 v189, 0xffff0000, v26
	v_fmac_f32_e32 v155, 0xbaaaaaab, v77
	v_fmac_f32_e32 v189, 0xbaaaaaab, v77
	v_mul_f32_e32 v155, v155, v154
	v_mul_f32_e32 v189, v189, v154
	v_fma_f32 v155, v204, v155, v212
	v_fma_f32 v189, v205, v189, v213
	v_cvt_pk_bf16_f32 v26, v155, v189
	ds_write_b16 v86, v26 offset:5440
	ds_write_b16_d16_hi v86, v26 offset:5712
	v_lshlrev_b32_e32 v155, 16, v27
	v_and_b32_e32 v189, 0xffff0000, v27
	v_fmac_f32_e32 v155, 0xbaaaaaab, v77
	v_fmac_f32_e32 v189, 0xbaaaaaab, v77
	v_mul_f32_e32 v155, v155, v154
	v_mul_f32_e32 v189, v189, v154
	v_fma_f32 v155, v206, v155, v214
	v_fma_f32 v189, v207, v189, v215
	v_cvt_pk_bf16_f32 v27, v155, v189
	ds_write_b16 v86, v27 offset:5984
	ds_write_b16_d16_hi v86, v27 offset:6256
	s_waitcnt lgkmcnt(0)
	v_lshlrev_b32_e32 v155, 16, v28
	v_and_b32_e32 v189, 0xffff0000, v28
	v_fmac_f32_e32 v155, 0xbaaaaaab, v77
	v_fmac_f32_e32 v189, 0xbaaaaaab, v77
	v_mul_f32_e32 v155, v155, v154
	v_mul_f32_e32 v189, v189, v154
	v_fma_f32 v155, v216, v155, v224
	v_fma_f32 v189, v217, v189, v225
	v_cvt_pk_bf16_f32 v28, v155, v189
	ds_write_b16 v86, v28 offset:6528
	ds_write_b16_d16_hi v86, v28 offset:6800
	v_lshlrev_b32_e32 v155, 16, v29
	v_and_b32_e32 v189, 0xffff0000, v29
	v_fmac_f32_e32 v155, 0xbaaaaaab, v77
	v_fmac_f32_e32 v189, 0xbaaaaaab, v77
	v_mul_f32_e32 v155, v155, v154
	v_mul_f32_e32 v189, v189, v154
	v_fma_f32 v155, v218, v155, v226
	v_fma_f32 v189, v219, v189, v227
	v_cvt_pk_bf16_f32 v29, v155, v189
	ds_write_b16 v86, v29 offset:7072
	ds_write_b16_d16_hi v86, v29 offset:7344
	v_lshlrev_b32_e32 v155, 16, v30
	v_and_b32_e32 v189, 0xffff0000, v30
	v_fmac_f32_e32 v155, 0xbaaaaaab, v77
	v_fmac_f32_e32 v189, 0xbaaaaaab, v77
	v_mul_f32_e32 v155, v155, v154
	v_mul_f32_e32 v189, v189, v154
	v_fma_f32 v155, v220, v155, v228
	v_fma_f32 v189, v221, v189, v229
	v_cvt_pk_bf16_f32 v30, v155, v189
	ds_write_b16 v86, v30 offset:7616
	ds_write_b16_d16_hi v86, v30 offset:7888
	v_lshlrev_b32_e32 v155, 16, v31
	v_and_b32_e32 v189, 0xffff0000, v31
	v_fmac_f32_e32 v155, 0xbaaaaaab, v77
	v_fmac_f32_e32 v189, 0xbaaaaaab, v77
	v_mul_f32_e32 v155, v155, v154
	v_mul_f32_e32 v189, v189, v154
	v_fma_f32 v155, v222, v155, v230
	v_fma_f32 v189, v223, v189, v231
	v_cvt_pk_bf16_f32 v31, v155, v189
	ds_write_b16 v86, v31 offset:8160
	ds_write_b16_d16_hi v86, v31 offset:8432
	s_waitcnt lgkmcnt(0)
	s_barrier
	s_waitcnt vmcnt(20)
	ds_read_b128 v[200:203], v87 offset:0
	ds_read_b128 v[204:207], v87 offset:64
	ds_read_b128 v[208:211], v87 offset:128
	ds_read_b128 v[212:215], v87 offset:192
	ds_read_b128 v[216:219], v87 offset:1088
	ds_read_b128 v[220:223], v87 offset:1152
	ds_read_b128 v[224:227], v87 offset:1216
	ds_read_b128 v[228:231], v87 offset:1280
	s_waitcnt lgkmcnt(4)
	v_mfma_f32_16x16x32_bf16 v[78:81], v[200:203], v[32:35], 0
	v_mfma_f32_16x16x32_bf16 v[78:81], v[204:207], v[36:39], v[78:81]
	v_mfma_f32_16x16x32_bf16 v[78:81], v[208:211], v[40:43], v[78:81]
	v_mfma_f32_16x16x32_bf16 v[78:81], v[212:215], v[44:47], v[78:81]
	ds_read_b128 v[200:203], v87 offset:8704
	ds_read_b128 v[204:207], v87 offset:8768
	ds_read_b128 v[208:211], v87 offset:8832
	ds_read_b128 v[212:215], v87 offset:8896
	s_waitcnt lgkmcnt(4)
	v_mfma_f32_16x16x32_bf16 v[94:97], v[216:219], v[32:35], 0
	v_mfma_f32_16x16x32_bf16 v[94:97], v[220:223], v[36:39], v[94:97]
	v_mfma_f32_16x16x32_bf16 v[94:97], v[224:227], v[40:43], v[94:97]
	v_mfma_f32_16x16x32_bf16 v[94:97], v[228:231], v[44:47], v[94:97]
	ds_read_b128 v[216:219], v87 offset:9792
	ds_read_b128 v[220:223], v87 offset:9856
	ds_read_b128 v[224:227], v87 offset:9920
	ds_read_b128 v[228:231], v87 offset:9984
	s_waitcnt lgkmcnt(4)
	v_mfma_f32_16x16x32_bf16 v[142:145], v[200:203], v[32:35], 0
	v_mfma_f32_16x16x32_bf16 v[142:145], v[204:207], v[36:39], v[142:145]
	v_mfma_f32_16x16x32_bf16 v[142:145], v[208:211], v[40:43], v[142:145]
	v_mfma_f32_16x16x32_bf16 v[142:145], v[212:215], v[44:47], v[142:145]
	ds_read_b128 v[200:203], v87 offset:17408
	ds_read_b128 v[204:207], v87 offset:17472
	ds_read_b128 v[208:211], v87 offset:17536
	ds_read_b128 v[212:215], v87 offset:17600
	v_add_f32_e32 v78, v64, v78
	v_add_f32_e32 v79, v64, v79
	v_add_f32_e32 v80, v64, v80
	v_add_f32_e32 v81, v64, v81
	v_lshlrev_b32_e32 v155, 16, v48
	v_and_b32_e32 v189, 0xffff0000, v48
	v_mul_f32_e32 v78, v78, v155
	v_mul_f32_e32 v79, v79, v189
	v_lshlrev_b32_e32 v155, 16, v49
	v_and_b32_e32 v189, 0xffff0000, v49
	v_mul_f32_e32 v80, v80, v155
	v_mul_f32_e32 v81, v81, v189
	v_cvt_pk_bf16_f32 v48, v78, v79
	v_cvt_pk_bf16_f32 v49, v80, v81
	v_add_f32_e32 v94, v64, v94
	v_add_f32_e32 v95, v64, v95
	v_add_f32_e32 v96, v64, v96
	v_add_f32_e32 v97, v64, v97
	v_lshlrev_b32_e32 v155, 16, v50
	v_and_b32_e32 v189, 0xffff0000, v50
	v_mul_f32_e32 v94, v94, v155
	v_mul_f32_e32 v95, v95, v189
	v_lshlrev_b32_e32 v155, 16, v51
	v_and_b32_e32 v189, 0xffff0000, v51
	v_mul_f32_e32 v96, v96, v155
	v_mul_f32_e32 v97, v97, v189
	v_cvt_pk_bf16_f32 v50, v94, v95
	v_cvt_pk_bf16_f32 v51, v96, v97
	global_store_dwordx4 v93, v[48:51], s[68:69]
	s_waitcnt lgkmcnt(4)
	v_mfma_f32_16x16x32_bf16 v[146:149], v[216:219], v[32:35], 0
	v_mfma_f32_16x16x32_bf16 v[146:149], v[220:223], v[36:39], v[146:149]
	v_mfma_f32_16x16x32_bf16 v[146:149], v[224:227], v[40:43], v[146:149]
	v_mfma_f32_16x16x32_bf16 v[146:149], v[228:231], v[44:47], v[146:149]
	ds_read_b128 v[216:219], v87 offset:18496
	ds_read_b128 v[220:223], v87 offset:18560
	ds_read_b128 v[224:227], v87 offset:18624
	ds_read_b128 v[228:231], v87 offset:18688
	s_waitcnt lgkmcnt(4)
	v_mfma_f32_16x16x32_bf16 v[78:81], v[200:203], v[32:35], 0
	v_mfma_f32_16x16x32_bf16 v[78:81], v[204:207], v[36:39], v[78:81]
	v_mfma_f32_16x16x32_bf16 v[78:81], v[208:211], v[40:43], v[78:81]
	v_mfma_f32_16x16x32_bf16 v[78:81], v[212:215], v[44:47], v[78:81]
	ds_read_b128 v[200:203], v87 offset:26112
	ds_read_b128 v[204:207], v87 offset:26176
	ds_read_b128 v[208:211], v87 offset:26240
	ds_read_b128 v[212:215], v87 offset:26304
	v_add_f32_e32 v142, v64, v142
	v_add_f32_e32 v143, v64, v143
	v_add_f32_e32 v144, v64, v144
	v_add_f32_e32 v145, v64, v145
	v_lshlrev_b32_e32 v155, 16, v52
	v_and_b32_e32 v189, 0xffff0000, v52
	v_mul_f32_e32 v142, v142, v155
	v_mul_f32_e32 v143, v143, v189
	v_lshlrev_b32_e32 v155, 16, v53
	v_and_b32_e32 v189, 0xffff0000, v53
	v_mul_f32_e32 v144, v144, v155
	v_mul_f32_e32 v145, v145, v189
	v_cvt_pk_bf16_f32 v52, v142, v143
	v_cvt_pk_bf16_f32 v53, v144, v145
	v_add_f32_e32 v146, v64, v146
	v_add_f32_e32 v147, v64, v147
	v_add_f32_e32 v148, v64, v148
	v_add_f32_e32 v149, v64, v149
	v_lshlrev_b32_e32 v155, 16, v54
	v_and_b32_e32 v189, 0xffff0000, v54
	v_mul_f32_e32 v146, v146, v155
	v_mul_f32_e32 v147, v147, v189
	v_lshlrev_b32_e32 v155, 16, v55
	v_and_b32_e32 v189, 0xffff0000, v55
	v_mul_f32_e32 v148, v148, v155
	v_mul_f32_e32 v149, v149, v189
	v_cvt_pk_bf16_f32 v54, v146, v147
	v_cvt_pk_bf16_f32 v55, v148, v149
	global_store_dwordx4 v93, v[52:55], s[68:69] offset:64
	s_waitcnt lgkmcnt(4)
	v_mfma_f32_16x16x32_bf16 v[94:97], v[216:219], v[32:35], 0
	v_mfma_f32_16x16x32_bf16 v[94:97], v[220:223], v[36:39], v[94:97]
	v_mfma_f32_16x16x32_bf16 v[94:97], v[224:227], v[40:43], v[94:97]
	v_mfma_f32_16x16x32_bf16 v[94:97], v[228:231], v[44:47], v[94:97]
	ds_read_b128 v[216:219], v87 offset:27200
	ds_read_b128 v[220:223], v87 offset:27264
	ds_read_b128 v[224:227], v87 offset:27328
	ds_read_b128 v[228:231], v87 offset:27392
	s_waitcnt lgkmcnt(4)
	v_mfma_f32_16x16x32_bf16 v[142:145], v[200:203], v[32:35], 0
	v_mfma_f32_16x16x32_bf16 v[142:145], v[204:207], v[36:39], v[142:145]
	v_mfma_f32_16x16x32_bf16 v[142:145], v[208:211], v[40:43], v[142:145]
	v_mfma_f32_16x16x32_bf16 v[142:145], v[212:215], v[44:47], v[142:145]
	v_add_f32_e32 v78, v64, v78
	v_add_f32_e32 v79, v64, v79
	v_add_f32_e32 v80, v64, v80
	v_add_f32_e32 v81, v64, v81
	v_lshlrev_b32_e32 v155, 16, v56
	v_and_b32_e32 v189, 0xffff0000, v56
	v_mul_f32_e32 v78, v78, v155
	v_mul_f32_e32 v79, v79, v189
	v_lshlrev_b32_e32 v155, 16, v57
	v_and_b32_e32 v189, 0xffff0000, v57
	v_mul_f32_e32 v80, v80, v155
	v_mul_f32_e32 v81, v81, v189
	v_cvt_pk_bf16_f32 v56, v78, v79
	v_cvt_pk_bf16_f32 v57, v80, v81
	v_add_f32_e32 v94, v64, v94
	v_add_f32_e32 v95, v64, v95
	v_add_f32_e32 v96, v64, v96
	v_add_f32_e32 v97, v64, v97
	v_lshlrev_b32_e32 v155, 16, v58
	v_and_b32_e32 v189, 0xffff0000, v58
	v_mul_f32_e32 v94, v94, v155
	v_mul_f32_e32 v95, v95, v189
	v_lshlrev_b32_e32 v155, 16, v59
	v_and_b32_e32 v189, 0xffff0000, v59
	v_mul_f32_e32 v96, v96, v155
	v_mul_f32_e32 v97, v97, v189
	v_cvt_pk_bf16_f32 v58, v94, v95
	v_cvt_pk_bf16_f32 v59, v96, v97
	global_store_dwordx4 v93, v[56:59], s[68:69] offset:128
	s_waitcnt lgkmcnt(0)
	v_mfma_f32_16x16x32_bf16 v[146:149], v[216:219], v[32:35], 0
	v_mfma_f32_16x16x32_bf16 v[146:149], v[220:223], v[36:39], v[146:149]
	v_mfma_f32_16x16x32_bf16 v[146:149], v[224:227], v[40:43], v[146:149]
	v_mfma_f32_16x16x32_bf16 v[146:149], v[228:231], v[44:47], v[146:149]
	s_nop 7
	v_add_f32_e32 v142, v64, v142
	v_add_f32_e32 v143, v64, v143
	v_add_f32_e32 v144, v64, v144
	v_add_f32_e32 v145, v64, v145
	v_lshlrev_b32_e32 v155, 16, v60
	v_and_b32_e32 v189, 0xffff0000, v60
	v_mul_f32_e32 v142, v142, v155
	v_mul_f32_e32 v143, v143, v189
	v_lshlrev_b32_e32 v155, 16, v61
	v_and_b32_e32 v189, 0xffff0000, v61
	v_mul_f32_e32 v144, v144, v155
	v_mul_f32_e32 v145, v145, v189
	v_cvt_pk_bf16_f32 v60, v142, v143
	v_cvt_pk_bf16_f32 v61, v144, v145
	v_add_f32_e32 v146, v64, v146
	v_add_f32_e32 v147, v64, v147
	v_add_f32_e32 v148, v64, v148
	v_add_f32_e32 v149, v64, v149
	v_lshlrev_b32_e32 v155, 16, v62
	v_and_b32_e32 v189, 0xffff0000, v62
	v_mul_f32_e32 v146, v146, v155
	v_mul_f32_e32 v147, v147, v189
	v_lshlrev_b32_e32 v155, 16, v63
	v_and_b32_e32 v189, 0xffff0000, v63
	v_mul_f32_e32 v148, v148, v155
	v_mul_f32_e32 v149, v149, v189
	v_cvt_pk_bf16_f32 v62, v146, v147
	v_cvt_pk_bf16_f32 v63, v148, v149
	global_store_dwordx4 v93, v[60:63], s[68:69] offset:192
	s_barrier
	s_mov_b32 s16, s70
	s_cmpk_lt_u32 s16, 0x600
	s_cbranch_scc0 .Lgm_done
	s_branch .Lgm_loop
